# latent attention: persistent -m SrcC blocks replace per-tile v_xor+15 v_mov broadcast (68 VALU/iter), hazard nops
# speedup vs baseline: 1.0164x; 1.0088x over previous
.LBB0_880:
	v_xor_b32_e32 v194, 0x80000000, v169
	v_mov_b32_e32 v195, v194
	v_mov_b32_e32 v196, v194
	v_mov_b32_e32 v197, v194
	v_mov_b32_e32 v198, v194
	v_mov_b32_e32 v199, v194
	v_mov_b32_e32 v200, v194
	v_mov_b32_e32 v201, v194
	v_mov_b32_e32 v202, v194
	v_mov_b32_e32 v203, v194
	v_mov_b32_e32 v204, v194
	v_mov_b32_e32 v205, v194
	v_mov_b32_e32 v206, v194
	v_mov_b32_e32 v207, v194
	v_mov_b32_e32 v208, v194
	v_mov_b32_e32 v209, v194
	v_and_or_b32 v1, v212, 14, v152
	v_lshlrev_b32_e32 v161, 3, v1
	v_add_u32_e32 v1, v159, v161
	v_xor_b32_e32 v162, 16, v161
	v_exp_f32_e32 v88, v10
	v_exp_f32_e32 v89, v11
	v_exp_f32_e32 v90, v12
	v_exp_f32_e32 v91, v13
	ds_read2st64_b64 v[10:13], v1 offset0:16 offset1:24
	v_add_u32_e32 v1, v159, v162
	ds_read2st64_b64 v[64:67], v1 offset0:16 offset1:24
	v_exp_f32_e32 v76, v2
	v_exp_f32_e32 v77, v3
	v_exp_f32_e32 v78, v4
	v_exp_f32_e32 v79, v5
	v_exp_f32_e32 v84, v6
	v_exp_f32_e32 v85, v7
	v_exp_f32_e32 v86, v8
	v_exp_f32_e32 v87, v9
	s_waitcnt lgkmcnt(0)
	v_mov_b32_e32 v68, v10
	v_mov_b32_e32 v69, v11
	v_mov_b32_e32 v70, v64
	v_mov_b32_e32 v71, v65
	v_xor_b32_e32 v163, 32, v161
	v_mov_b32_e32 v64, v12
	v_mov_b32_e32 v65, v13
	v_add_u32_e32 v1, v159, v163
	v_xor_b32_e32 v164, 48, v161
	ds_read2st64_b64 v[112:115], v1 offset0:16 offset1:24
	v_add_u32_e32 v1, v159, v164
	ds_read2st64_b64 v[80:83], v1 offset0:16 offset1:24
	v_cvt_pkrtz_f16_f32 v2, v76, v77
	v_cvt_pkrtz_f16_f32 v3, v78, v79
	v_cvt_pkrtz_f16_f32 v4, v84, v85
	v_cvt_pkrtz_f16_f32 v5, v86, v87
	v_exp_f32_e32 v94, v16
	v_exp_f32_e32 v95, v17
	v_mfma_f32_32x32x16_f16 v[16:31], v[68:71], v[2:5], 0
	v_exp_f32_e32 v92, v14
	v_exp_f32_e32 v93, v15
	s_waitcnt lgkmcnt(0)
	v_mov_b32_e32 v72, v112
	v_mov_b32_e32 v73, v113
	v_mov_b32_e32 v74, v80
	v_mov_b32_e32 v75, v81
	v_mov_b32_e32 v80, v114
	v_mfma_f32_32x32x16_f16 v[32:47], v[64:67], v[2:5], 0
	v_mov_b32_e32 v81, v115
	v_add_u32_e32 v143, v159, v156
	ds_read_b128 v[170:173], v143 offset:4096
	ds_read_b128 v[128:131], v154 offset:16384
	v_cvt_pkrtz_f16_f32 v6, v88, v89
	v_cvt_pkrtz_f16_f32 v7, v90, v91
	v_cvt_pkrtz_f16_f32 v8, v92, v93
	v_cvt_pkrtz_f16_f32 v9, v94, v95
	v_mov_b32_e32 v14, v0
	v_mov_b32_e32 v15, v0
	v_mfma_f32_32x32x16_f16 v[16:31], v[72:75], v[6:9], v[16:31]
	v_mov_b32_e32 v1, v0
	v_mov_b32_e32 v2, v0
	v_mov_b32_e32 v3, v0
	v_mov_b32_e32 v4, v0
	v_mov_b32_e32 v5, v0
	v_mov_b32_e32 v10, v0
	v_mov_b32_e32 v11, v0
	v_mfma_f32_32x32x16_f16 v[32:47], v[80:83], v[6:9], v[32:47]
	v_mov_b32_e32 v6, v0
	v_mov_b32_e32 v7, v0
	v_mov_b32_e32 v8, v0
	v_mov_b32_e32 v9, v0
	v_mov_b32_e32 v12, v0
	v_mov_b32_e32 v13, v0
	v_mov_b64_e32 v[126:127], v[14:15]
	v_mov_b64_e32 v[124:125], v[12:13]
	v_mov_b64_e32 v[122:123], v[10:11]
	v_mov_b64_e32 v[120:121], v[8:9]
	v_mov_b64_e32 v[118:119], v[6:7]
	v_mov_b64_e32 v[116:117], v[4:5]
	v_mov_b64_e32 v[114:115], v[2:3]
	v_mov_b64_e32 v[112:113], v[0:1]
	v_add_u32_e32 v15, v159, v155
	ds_read_b128 v[6:9], v15 offset:4096
	ds_read_b128 v[2:5], v154 offset:24576
	s_waitcnt lgkmcnt(0)
	v_mfma_f32_32x32x16_f16 v[112:127], v[170:173], v[128:131], v[112:127]
	v_max_f32_e32 v1, v49, v49
	s_cmp_eq_u64 exec, 0
	v_mfma_f32_32x32x16_f16 v[112:127], v[6:9], v[2:5], v[112:127]
	v_max_f32_e32 v6, v48, v48
	v_max_f32_e32 v1, v6, v1
	v_max3_f32 v1, v1, v50, v51
	v_max3_f32 v1, v1, v52, v53
	v_max3_f32 v1, v1, v54, v55
	v_max3_f32 v1, v1, v56, v57
	v_max3_f32 v1, v1, v58, v59
	v_max3_f32 v1, v1, v60, v61
	v_max3_f32 v1, v1, v62, v63
	ds_bpermute_b32 v6, v153, v1
	s_cbranch_scc1 .LBB0_882
	s_waitcnt lgkmcnt(0)
	v_max_f32_e32 v6, v6, v6
	v_max_f32_e32 v1, v1, v1
	v_max_f32_e32 v6, v1, v6
	v_add_f32_e32 v168, 0, v6
	v_pk_add_f32 v[48:49], v[48:49], v[6:7] op_sel_hi:[1,0] neg_lo:[0,1] neg_hi:[0,1]
	v_pk_add_f32 v[50:51], v[50:51], v[6:7] op_sel_hi:[1,0] neg_lo:[0,1] neg_hi:[0,1]
	v_pk_add_f32 v[52:53], v[52:53], v[6:7] op_sel_hi:[1,0] neg_lo:[0,1] neg_hi:[0,1]
	v_pk_add_f32 v[54:55], v[54:55], v[6:7] op_sel_hi:[1,0] neg_lo:[0,1] neg_hi:[0,1]
	v_pk_add_f32 v[56:57], v[56:57], v[6:7] op_sel_hi:[1,0] neg_lo:[0,1] neg_hi:[0,1]
	v_pk_add_f32 v[58:59], v[58:59], v[6:7] op_sel_hi:[1,0] neg_lo:[0,1] neg_hi:[0,1]
	v_pk_add_f32 v[60:61], v[60:61], v[6:7] op_sel_hi:[1,0] neg_lo:[0,1] neg_hi:[0,1]
	v_pk_add_f32 v[62:63], v[62:63], v[6:7] op_sel_hi:[1,0] neg_lo:[0,1] neg_hi:[0,1]
	v_sub_f32_e32 v127, v127, v6
	v_sub_f32_e32 v126, v126, v6
	v_sub_f32_e32 v125, v125, v6
	v_sub_f32_e32 v124, v124, v6
	v_sub_f32_e32 v123, v123, v6
	v_sub_f32_e32 v122, v122, v6
	v_sub_f32_e32 v121, v121, v6
	v_sub_f32_e32 v120, v120, v6
	v_sub_f32_e32 v119, v119, v6
	v_sub_f32_e32 v118, v118, v6
	v_sub_f32_e32 v117, v117, v6
	v_sub_f32_e32 v116, v116, v6
	v_sub_f32_e32 v115, v115, v6
	v_sub_f32_e32 v114, v114, v6
	v_sub_f32_e32 v113, v113, v6
	v_sub_f32_e32 v112, v112, v6
	s_branch .LBB0_883

.LBB0_883:
	v_xor_b32_e32 v230, 0x80000000, v168
	v_mov_b32_e32 v231, v230
	v_mov_b32_e32 v232, v230
	v_mov_b32_e32 v233, v230
	v_mov_b32_e32 v234, v230
	v_mov_b32_e32 v235, v230
	v_mov_b32_e32 v236, v230
	v_mov_b32_e32 v237, v230
	v_mov_b32_e32 v238, v230
	v_mov_b32_e32 v239, v230
	v_mov_b32_e32 v240, v230
	v_mov_b32_e32 v241, v230
	v_mov_b32_e32 v242, v230
	v_mov_b32_e32 v243, v230
	v_mov_b32_e32 v244, v230
	v_mov_b32_e32 v245, v230
	v_add_f32_e32 v1, 0, v76
	v_add_f32_e32 v1, v77, v1
	v_add_f32_e32 v1, v78, v1
	v_add_f32_e32 v1, v79, v1
	v_add_f32_e32 v1, v84, v1
	v_add_f32_e32 v1, v85, v1
	v_add_f32_e32 v1, v86, v1
	v_add_f32_e32 v1, v87, v1
	v_add_f32_e32 v1, v88, v1
	v_add_f32_e32 v1, v89, v1
	v_add_f32_e32 v1, v90, v1
	v_add_f32_e32 v1, v91, v1
	v_add_f32_e32 v1, v92, v1
	v_add_f32_e32 v1, v93, v1
	v_add_f32_e32 v1, v94, v1
	v_add_f32_e32 v1, v95, v1
	v_add_f32_e32 v14, 0, v1
	v_exp_f32_e32 v1, v48
	s_waitcnt lgkmcnt(0)
	v_exp_f32_e32 v6, v49
	v_exp_f32_e32 v7, v50
	v_exp_f32_e32 v8, v51
	v_exp_f32_e32 v9, v52
	v_exp_f32_e32 v10, v53
	v_exp_f32_e32 v174, v54
	v_exp_f32_e32 v170, v55
	v_cvt_pkrtz_f16_f32 v76, v1, v6
	v_cvt_pkrtz_f16_f32 v77, v7, v8
	v_cvt_pkrtz_f16_f32 v78, v9, v10
	v_cvt_pkrtz_f16_f32 v79, v174, v170
	v_exp_f32_e32 v171, v56
	v_exp_f32_e32 v172, v57
	v_exp_f32_e32 v173, v58
	v_exp_f32_e32 v151, v59
	v_exp_f32_e32 v145, v60
	v_exp_f32_e32 v146, v61
	v_exp_f32_e32 v147, v62
	v_exp_f32_e32 v150, v63
	v_mfma_f32_32x32x16_f16 v[48:63], v[68:71], v[76:79], 0
	v_cvt_pkrtz_f16_f32 v84, v171, v172
	v_cvt_pkrtz_f16_f32 v85, v173, v151
	v_cvt_pkrtz_f16_f32 v86, v145, v146
	v_cvt_pkrtz_f16_f32 v87, v147, v150
	v_add_u32_e32 v11, v159, v158
	ds_read_b128 v[176:179], v11 offset:16384
	v_add_u32_e32 v11, v159, v160
	v_mfma_f32_32x32x16_f16 v[48:63], v[72:75], v[84:87], v[48:63]
	v_max_f32_e32 v12, v96, v96
	v_mfma_f32_32x32x16_f16 v[64:79], v[64:67], v[76:79], 0
	v_mfma_f32_32x32x16_f16 v[64:79], v[80:83], v[84:87], v[64:79]
	s_waitcnt lgkmcnt(0)
	s_nop 0
	v_mfma_f32_32x32x16_f16 v[80:95], v[176:179], v[136:139], v[194:209]
	ds_read_b128 v[136:139], v11 offset:16384
	v_max_f32_e32 v11, v97, v97
	v_max_f32_e32 v11, v12, v11
	v_max3_f32 v11, v11, v98, v99
	v_max3_f32 v11, v11, v100, v101
	v_max3_f32 v11, v11, v102, v103
	v_max3_f32 v11, v11, v104, v105
	v_max3_f32 v11, v11, v106, v107
	v_max3_f32 v11, v11, v108, v109
	v_max3_f32 v11, v11, v110, v111
	s_waitcnt lgkmcnt(0)
	v_mfma_f32_32x32x16_f16 v[80:95], v[136:139], v[132:135], v[80:95]
	ds_bpermute_b32 v12, v153, v11
	s_waitcnt lgkmcnt(0)
	v_max_f32_e32 v12, v12, v12
	v_max_f32_e32 v11, v11, v12
	v_cmp_lt_f32_e32 vcc, s61, v11
	s_cbranch_vccz .LBB0_885
	v_max_f32_e32 v11, v11, v11
	v_max_f32_e32 v12, 0, v11
	v_exp_f32_e64 v132, -v12
	v_add_f32_e32 v169, v169, v12
	v_pk_add_f32 v[96:97], v[96:97], v[12:13] op_sel_hi:[1,0] neg_lo:[0,1] neg_hi:[0,1]
	v_pk_add_f32 v[98:99], v[98:99], v[12:13] op_sel_hi:[1,0] neg_lo:[0,1] neg_hi:[0,1]
	v_mul_f32_e32 v14, v14, v132
	v_pk_add_f32 v[100:101], v[100:101], v[12:13] op_sel_hi:[1,0] neg_lo:[0,1] neg_hi:[0,1]
	v_pk_add_f32 v[102:103], v[102:103], v[12:13] op_sel_hi:[1,0] neg_lo:[0,1] neg_hi:[0,1]
	v_pk_add_f32 v[104:105], v[104:105], v[12:13] op_sel_hi:[1,0] neg_lo:[0,1] neg_hi:[0,1]
	v_pk_add_f32 v[106:107], v[106:107], v[12:13] op_sel_hi:[1,0] neg_lo:[0,1] neg_hi:[0,1]
	v_pk_add_f32 v[108:109], v[108:109], v[12:13] op_sel_hi:[1,0] neg_lo:[0,1] neg_hi:[0,1]
	v_pk_add_f32 v[110:111], v[110:111], v[12:13] op_sel_hi:[1,0] neg_lo:[0,1] neg_hi:[0,1]
	v_sub_f32_e32 v95, v95, v12
	v_sub_f32_e32 v94, v94, v12
	v_sub_f32_e32 v93, v93, v12
	v_sub_f32_e32 v92, v92, v12
	v_sub_f32_e32 v91, v91, v12
	v_sub_f32_e32 v90, v90, v12
	v_sub_f32_e32 v89, v89, v12
	v_sub_f32_e32 v88, v88, v12
	v_sub_f32_e32 v87, v87, v12
	v_sub_f32_e32 v86, v86, v12
	v_sub_f32_e32 v85, v85, v12
	v_sub_f32_e32 v84, v84, v12
	v_sub_f32_e32 v83, v83, v12
	v_sub_f32_e32 v82, v82, v12
	v_sub_f32_e32 v81, v81, v12
	v_sub_f32_e32 v80, v80, v12
	v_pk_mul_f32 v[30:31], v[30:31], v[132:133] op_sel_hi:[1,0]
	v_pk_mul_f32 v[28:29], v[28:29], v[132:133] op_sel_hi:[1,0]
	v_pk_mul_f32 v[26:27], v[26:27], v[132:133] op_sel_hi:[1,0]
	v_pk_mul_f32 v[24:25], v[24:25], v[132:133] op_sel_hi:[1,0]
	v_pk_mul_f32 v[22:23], v[22:23], v[132:133] op_sel_hi:[1,0]
	v_pk_mul_f32 v[20:21], v[20:21], v[132:133] op_sel_hi:[1,0]
	v_pk_mul_f32 v[18:19], v[18:19], v[132:133] op_sel_hi:[1,0]
	v_pk_mul_f32 v[16:17], v[16:17], v[132:133] op_sel_hi:[1,0]
	v_pk_mul_f32 v[46:47], v[46:47], v[132:133] op_sel_hi:[1,0]
	v_pk_mul_f32 v[44:45], v[44:45], v[132:133] op_sel_hi:[1,0]
	v_pk_mul_f32 v[42:43], v[42:43], v[132:133] op_sel_hi:[1,0]
	v_pk_mul_f32 v[40:41], v[40:41], v[132:133] op_sel_hi:[1,0]
	v_pk_mul_f32 v[38:39], v[38:39], v[132:133] op_sel_hi:[1,0]
	v_pk_mul_f32 v[36:37], v[36:37], v[132:133] op_sel_hi:[1,0]
	v_pk_mul_f32 v[34:35], v[34:35], v[132:133] op_sel_hi:[1,0]
	v_pk_mul_f32 v[32:33], v[32:33], v[132:133] op_sel_hi:[1,0]
	v_sub_f32_e32 v194, v194, v12
	v_sub_f32_e32 v195, v195, v12
	v_sub_f32_e32 v196, v196, v12
	v_sub_f32_e32 v197, v197, v12
	v_sub_f32_e32 v198, v198, v12
	v_sub_f32_e32 v199, v199, v12
	v_sub_f32_e32 v200, v200, v12
	v_sub_f32_e32 v201, v201, v12
	v_sub_f32_e32 v202, v202, v12
	v_sub_f32_e32 v203, v203, v12
	v_sub_f32_e32 v204, v204, v12
	v_sub_f32_e32 v205, v205, v12
	v_sub_f32_e32 v206, v206, v12
	v_sub_f32_e32 v207, v207, v12
	v_sub_f32_e32 v208, v208, v12
	v_sub_f32_e32 v209, v209, v12
	s_nop 1
.LBB0_885:
	v_add_f32_e32 v1, 0, v1
	v_add_f32_e32 v1, v6, v1
	v_add_f32_e32 v1, v7, v1
	v_add_f32_e32 v1, v8, v1
	v_add_f32_e32 v1, v9, v1
	v_xor_b32_e32 v166, 64, v161
	v_add_f32_e32 v191, v10, v1
	v_add_u32_e32 v1, v159, v166
	v_xor_b32_e32 v167, 0x50, v161
	v_exp_f32_e32 v179, v100
	v_exp_f32_e32 v180, v101
	v_exp_f32_e32 v181, v102
	v_exp_f32_e32 v182, v103
	ds_read2st64_b64 v[100:103], v1 offset0:16 offset1:24
	v_add_u32_e32 v1, v159, v167
	ds_read2st64_b64 v[10:13], v1 offset0:16 offset1:24
	v_xor_b32_e32 v1, 0x60, v161
	v_add_u32_e32 v6, v159, v1
	v_xor_b32_e32 v165, 0x70, v161
	v_exp_f32_e32 v183, v104
	v_exp_f32_e32 v184, v105
	v_exp_f32_e32 v185, v106
	v_exp_f32_e32 v186, v107
	ds_read2st64_b64 v[104:107], v6 offset0:16 offset1:24
	v_add_u32_e32 v6, v159, v165
	ds_read2st64_b64 v[6:9], v6 offset0:16 offset1:24
	v_exp_f32_e32 v175, v96
	v_exp_f32_e32 v176, v97
	v_exp_f32_e32 v177, v98
	v_exp_f32_e32 v178, v99
	s_waitcnt lgkmcnt(0)
	v_mov_b32_e32 v136, v100
	v_mov_b32_e32 v137, v101
	v_mov_b32_e32 v138, v10
	v_mov_b32_e32 v139, v11
	v_mov_b32_e32 v10, v102
	v_mov_b32_e32 v11, v103
	v_mov_b32_e32 v134, v6
	v_add_f32_e32 v6, v174, v191
	v_add_f32_e32 v6, v170, v6
	v_add_f32_e32 v6, v171, v6
	v_cvt_pkrtz_f16_f32 v96, v175, v176
	v_cvt_pkrtz_f16_f32 v97, v177, v178
	v_cvt_pkrtz_f16_f32 v98, v179, v180
	v_cvt_pkrtz_f16_f32 v99, v181, v182
	v_add_f32_e32 v6, v172, v6
	v_add_f32_e32 v6, v173, v6
	v_mfma_f32_32x32x16_f16 v[16:31], v[136:139], v[96:99], v[16:31]
	ds_read_b128 v[170:173], v143 offset:16384
	v_exp_f32_e32 v187, v108
	v_exp_f32_e32 v188, v109
	v_exp_f32_e32 v189, v110
	v_exp_f32_e32 v190, v111
	v_mov_b32_e32 v132, v104
	v_mov_b32_e32 v133, v105
	v_mfma_f32_32x32x16_f16 v[32:47], v[10:13], v[96:99], v[32:47]
	v_mov_b32_e32 v135, v7
	v_add_f32_e32 v96, v151, v6
	v_mov_b32_e32 v6, v106
	v_mov_b32_e32 v7, v107
	v_add_f32_e32 v96, v145, v96
	v_add_f32_e32 v96, v146, v96
	v_add_f32_e32 v96, v147, v96
	v_cvt_pkrtz_f16_f32 v108, v183, v184
	v_cvt_pkrtz_f16_f32 v109, v185, v186
	v_cvt_pkrtz_f16_f32 v110, v187, v188
	v_cvt_pkrtz_f16_f32 v111, v189, v190
	v_add_f32_e32 v145, v150, v96
	s_nop 0
	v_mfma_f32_32x32x16_f16 v[16:31], v[132:135], v[108:111], v[16:31]
	v_mfma_f32_32x32x16_f16 v[32:47], v[6:9], v[108:111], v[32:47]
	v_max_f32_e32 v143, v112, v112
	s_waitcnt lgkmcnt(0)
	v_mfma_f32_32x32x16_f16 v[96:111], v[170:173], v[128:131], v[230:245]
	ds_read_b128 v[128:131], v15 offset:16384
	v_max_f32_e32 v15, v113, v113
	v_max_f32_e32 v15, v143, v15
	v_max3_f32 v15, v15, v114, v115
	v_max3_f32 v15, v15, v116, v117
	v_max3_f32 v15, v15, v118, v119
	v_max3_f32 v15, v15, v120, v121
	v_max3_f32 v15, v15, v122, v123
	v_max3_f32 v15, v15, v124, v125
	v_max3_f32 v143, v15, v126, v127
	ds_bpermute_b32 v146, v153, v143
	s_waitcnt lgkmcnt(0)
	v_mfma_f32_32x32x16_f16 v[96:111], v[128:131], v[2:5], v[96:111]
	v_add_f32_e32 v15, 0, v145
	v_max_f32_e32 v2, v146, v146
	v_max_f32_e32 v2, v143, v2
	v_cmp_lt_f32_e32 vcc, s61, v2
	s_cbranch_vccz .LBB0_887
	v_max_f32_e32 v2, v2, v2
	v_max_f32_e32 v2, 0, v2
	v_exp_f32_e64 v4, -v2
	v_add_f32_e32 v168, v168, v2
	v_pk_add_f32 v[112:113], v[112:113], v[2:3] op_sel_hi:[1,0] neg_lo:[0,1] neg_hi:[0,1]
	v_pk_add_f32 v[114:115], v[114:115], v[2:3] op_sel_hi:[1,0] neg_lo:[0,1] neg_hi:[0,1]
	v_mul_f32_e32 v15, v15, v4
	v_pk_add_f32 v[116:117], v[116:117], v[2:3] op_sel_hi:[1,0] neg_lo:[0,1] neg_hi:[0,1]
	v_pk_add_f32 v[118:119], v[118:119], v[2:3] op_sel_hi:[1,0] neg_lo:[0,1] neg_hi:[0,1]
	v_pk_add_f32 v[120:121], v[120:121], v[2:3] op_sel_hi:[1,0] neg_lo:[0,1] neg_hi:[0,1]
	v_pk_add_f32 v[122:123], v[122:123], v[2:3] op_sel_hi:[1,0] neg_lo:[0,1] neg_hi:[0,1]
	v_pk_add_f32 v[124:125], v[124:125], v[2:3] op_sel_hi:[1,0] neg_lo:[0,1] neg_hi:[0,1]
	v_pk_add_f32 v[126:127], v[126:127], v[2:3] op_sel_hi:[1,0] neg_lo:[0,1] neg_hi:[0,1]
	v_sub_f32_e32 v111, v111, v2
	v_sub_f32_e32 v110, v110, v2
	v_sub_f32_e32 v109, v109, v2
	v_sub_f32_e32 v108, v108, v2
	v_sub_f32_e32 v107, v107, v2
	v_sub_f32_e32 v106, v106, v2
	v_sub_f32_e32 v105, v105, v2
	v_sub_f32_e32 v104, v104, v2
	v_sub_f32_e32 v103, v103, v2
	v_sub_f32_e32 v102, v102, v2
	v_sub_f32_e32 v101, v101, v2
	v_sub_f32_e32 v100, v100, v2
	v_sub_f32_e32 v99, v99, v2
	v_sub_f32_e32 v98, v98, v2
	v_sub_f32_e32 v97, v97, v2
	v_sub_f32_e32 v96, v96, v2
	v_pk_mul_f32 v[62:63], v[62:63], v[4:5] op_sel_hi:[1,0]
	v_pk_mul_f32 v[60:61], v[60:61], v[4:5] op_sel_hi:[1,0]
	v_pk_mul_f32 v[58:59], v[58:59], v[4:5] op_sel_hi:[1,0]
	v_pk_mul_f32 v[56:57], v[56:57], v[4:5] op_sel_hi:[1,0]
	v_pk_mul_f32 v[54:55], v[54:55], v[4:5] op_sel_hi:[1,0]
	v_pk_mul_f32 v[52:53], v[52:53], v[4:5] op_sel_hi:[1,0]
	v_pk_mul_f32 v[50:51], v[50:51], v[4:5] op_sel_hi:[1,0]
	v_pk_mul_f32 v[48:49], v[48:49], v[4:5] op_sel_hi:[1,0]
	v_pk_mul_f32 v[78:79], v[78:79], v[4:5] op_sel_hi:[1,0]
	v_pk_mul_f32 v[76:77], v[76:77], v[4:5] op_sel_hi:[1,0]
	v_pk_mul_f32 v[74:75], v[74:75], v[4:5] op_sel_hi:[1,0]
	v_pk_mul_f32 v[72:73], v[72:73], v[4:5] op_sel_hi:[1,0]
	v_pk_mul_f32 v[70:71], v[70:71], v[4:5] op_sel_hi:[1,0]
	v_pk_mul_f32 v[68:69], v[68:69], v[4:5] op_sel_hi:[1,0]
	v_pk_mul_f32 v[66:67], v[66:67], v[4:5] op_sel_hi:[1,0]
	v_pk_mul_f32 v[64:65], v[64:65], v[4:5] op_sel_hi:[1,0]
	v_sub_f32_e32 v230, v230, v2
	v_sub_f32_e32 v231, v231, v2
	v_sub_f32_e32 v232, v232, v2
	v_sub_f32_e32 v233, v233, v2
	v_sub_f32_e32 v234, v234, v2
	v_sub_f32_e32 v235, v235, v2
	v_sub_f32_e32 v236, v236, v2
	v_sub_f32_e32 v237, v237, v2
	v_sub_f32_e32 v238, v238, v2
	v_sub_f32_e32 v239, v239, v2
	v_sub_f32_e32 v240, v240, v2
	v_sub_f32_e32 v241, v241, v2
	v_sub_f32_e32 v242, v242, v2
	v_sub_f32_e32 v243, v243, v2
	v_sub_f32_e32 v244, v244, v2
	v_sub_f32_e32 v245, v245, v2
	s_nop 1

.LBB0_892:
	v_lshl_or_b32 v172, s12, 14, v159
	v_add_u32_e32 v2, v172, v158
	ds_read_b128 v[2:5], v2 offset:4096
	ds_read_b128 v[144:147], v157 offset:49152
	s_waitcnt lgkmcnt(0)
	s_nop 0
	v_mfma_f32_32x32x16_f16 v[128:143], v[2:5], v[144:147], v[194:209]
	v_add_u32_e32 v2, v172, v160
	ds_read_b128 v[2:5], v2 offset:4096
	ds_read_b128 v[10:13], v157 offset:57344
	s_waitcnt lgkmcnt(0)
	v_mfma_f32_32x32x16_f16 v[128:143], v[2:5], v[10:13], v[128:143]
	v_max_f32_e32 v2, v81, v81
	v_max_f32_e32 v3, v80, v80
	v_max_f32_e32 v2, v3, v2
	v_max3_f32 v2, v2, v82, v83
	v_max3_f32 v2, v2, v84, v85
	v_max3_f32 v2, v2, v86, v87
	v_max3_f32 v2, v2, v88, v89
	v_max3_f32 v2, v2, v90, v91
	v_max3_f32 v2, v2, v92, v93
	v_max3_f32 v2, v2, v94, v95
	v_cmp_lt_f32_e32 vcc, s61, v2
	s_cbranch_vccz .LBB0_894
	ds_bpermute_b32 v3, v153, v2
	s_waitcnt lgkmcnt(0)
	v_max_f32_e32 v3, v3, v3
	v_max_f32_e32 v2, v2, v3
	v_max_f32_e32 v2, v2, v2
	v_max_f32_e32 v2, 0, v2
	v_exp_f32_e64 v4, -v2
	v_add_f32_e32 v169, v169, v2
	v_pk_add_f32 v[80:81], v[80:81], v[2:3] op_sel_hi:[1,0] neg_lo:[0,1] neg_hi:[0,1]
	v_pk_add_f32 v[82:83], v[82:83], v[2:3] op_sel_hi:[1,0] neg_lo:[0,1] neg_hi:[0,1]
	v_mul_f32_e32 v171, v171, v4
	v_pk_add_f32 v[84:85], v[84:85], v[2:3] op_sel_hi:[1,0] neg_lo:[0,1] neg_hi:[0,1]
	v_pk_add_f32 v[86:87], v[86:87], v[2:3] op_sel_hi:[1,0] neg_lo:[0,1] neg_hi:[0,1]
	v_pk_add_f32 v[88:89], v[88:89], v[2:3] op_sel_hi:[1,0] neg_lo:[0,1] neg_hi:[0,1]
	v_pk_add_f32 v[90:91], v[90:91], v[2:3] op_sel_hi:[1,0] neg_lo:[0,1] neg_hi:[0,1]
	v_pk_add_f32 v[92:93], v[92:93], v[2:3] op_sel_hi:[1,0] neg_lo:[0,1] neg_hi:[0,1]
	v_pk_add_f32 v[94:95], v[94:95], v[2:3] op_sel_hi:[1,0] neg_lo:[0,1] neg_hi:[0,1]
	v_sub_f32_e32 v143, v143, v2
	v_sub_f32_e32 v142, v142, v2
	v_sub_f32_e32 v141, v141, v2
	v_sub_f32_e32 v140, v140, v2
	v_sub_f32_e32 v139, v139, v2
	v_sub_f32_e32 v138, v138, v2
	v_sub_f32_e32 v137, v137, v2
	v_sub_f32_e32 v136, v136, v2
	v_sub_f32_e32 v135, v135, v2
	v_sub_f32_e32 v134, v134, v2
	v_sub_f32_e32 v133, v133, v2
	v_sub_f32_e32 v132, v132, v2
	v_sub_f32_e32 v131, v131, v2
	v_sub_f32_e32 v130, v130, v2
	v_sub_f32_e32 v129, v129, v2
	v_sub_f32_e32 v128, v128, v2
	v_pk_mul_f32 v[30:31], v[30:31], v[4:5] op_sel_hi:[1,0]
	v_pk_mul_f32 v[28:29], v[28:29], v[4:5] op_sel_hi:[1,0]
	v_pk_mul_f32 v[26:27], v[26:27], v[4:5] op_sel_hi:[1,0]
	v_pk_mul_f32 v[24:25], v[24:25], v[4:5] op_sel_hi:[1,0]
	v_pk_mul_f32 v[22:23], v[22:23], v[4:5] op_sel_hi:[1,0]
	v_pk_mul_f32 v[20:21], v[20:21], v[4:5] op_sel_hi:[1,0]
	v_pk_mul_f32 v[18:19], v[18:19], v[4:5] op_sel_hi:[1,0]
	v_pk_mul_f32 v[16:17], v[16:17], v[4:5] op_sel_hi:[1,0]
	v_pk_mul_f32 v[46:47], v[46:47], v[4:5] op_sel_hi:[1,0]
	v_pk_mul_f32 v[44:45], v[44:45], v[4:5] op_sel_hi:[1,0]
	v_pk_mul_f32 v[42:43], v[42:43], v[4:5] op_sel_hi:[1,0]
	v_pk_mul_f32 v[40:41], v[40:41], v[4:5] op_sel_hi:[1,0]
	v_pk_mul_f32 v[38:39], v[38:39], v[4:5] op_sel_hi:[1,0]
	v_pk_mul_f32 v[36:37], v[36:37], v[4:5] op_sel_hi:[1,0]
	v_pk_mul_f32 v[34:35], v[34:35], v[4:5] op_sel_hi:[1,0]
	v_pk_mul_f32 v[32:33], v[32:33], v[4:5] op_sel_hi:[1,0]
	v_sub_f32_e32 v194, v194, v2
	v_sub_f32_e32 v195, v195, v2
	v_sub_f32_e32 v196, v196, v2
	v_sub_f32_e32 v197, v197, v2
	v_sub_f32_e32 v198, v198, v2
	v_sub_f32_e32 v199, v199, v2
	v_sub_f32_e32 v200, v200, v2
	v_sub_f32_e32 v201, v201, v2
	v_sub_f32_e32 v202, v202, v2
	v_sub_f32_e32 v203, v203, v2
	v_sub_f32_e32 v204, v204, v2
	v_sub_f32_e32 v205, v205, v2
	v_sub_f32_e32 v206, v206, v2
	v_sub_f32_e32 v207, v207, v2
	v_sub_f32_e32 v208, v208, v2
	v_sub_f32_e32 v209, v209, v2
	s_nop 1
.LBB0_894:
	v_exp_f32_e32 v173, v80
	v_add_u32_e32 v80, v172, v161
	ds_read2st64_b64 v[112:115], v80 offset0:16 offset1:24
	v_add_u32_e32 v80, v172, v162
	v_exp_f32_e32 v177, v84
	v_exp_f32_e32 v178, v85
	v_exp_f32_e32 v179, v86
	v_exp_f32_e32 v180, v87
	ds_read2st64_b64 v[84:87], v80 offset0:16 offset1:24
	v_exp_f32_e32 v174, v81
	v_exp_f32_e32 v175, v82
	v_exp_f32_e32 v176, v83
	v_exp_f32_e32 v185, v92
	v_exp_f32_e32 v186, v93
	v_exp_f32_e32 v187, v94
	v_exp_f32_e32 v188, v95
	s_waitcnt lgkmcnt(0)
	v_mov_b32_e32 v92, v112
	v_mov_b32_e32 v93, v113
	v_mov_b32_e32 v94, v84
	v_mov_b32_e32 v95, v85
	v_mov_b32_e32 v84, v114
	v_mov_b32_e32 v85, v115
	v_add_u32_e32 v80, v172, v163
	ds_read2st64_b64 v[116:119], v80 offset0:16 offset1:24
	v_add_u32_e32 v80, v172, v164
	ds_read2st64_b64 v[80:83], v80 offset0:16 offset1:24
	v_cvt_pkrtz_f16_f32 v2, v173, v174
	v_cvt_pkrtz_f16_f32 v3, v175, v176
	v_cvt_pkrtz_f16_f32 v4, v177, v178
	v_cvt_pkrtz_f16_f32 v5, v179, v180
	v_exp_f32_e32 v181, v88
	v_exp_f32_e32 v182, v89
	v_mfma_f32_32x32x16_f16 v[16:31], v[92:95], v[2:5], v[16:31]
	v_exp_f32_e32 v183, v90
	v_exp_f32_e32 v184, v91
	s_waitcnt lgkmcnt(0)
	v_mov_b32_e32 v88, v116
	v_mov_b32_e32 v89, v117
	v_mov_b32_e32 v90, v80
	v_mov_b32_e32 v91, v81
	v_mov_b32_e32 v80, v118
	v_mfma_f32_32x32x16_f16 v[32:47], v[84:87], v[2:5], v[32:47]
	v_mov_b32_e32 v81, v119
	v_cvt_pkrtz_f16_f32 v6, v181, v182
	v_cvt_pkrtz_f16_f32 v7, v183, v184
	v_cvt_pkrtz_f16_f32 v8, v185, v186
	v_cvt_pkrtz_f16_f32 v9, v187, v188
	v_add_u32_e32 v2, v172, v156
	s_nop 0
	v_mfma_f32_32x32x16_f16 v[16:31], v[88:91], v[6:9], v[16:31]
	v_mfma_f32_32x32x16_f16 v[32:47], v[80:83], v[6:9], v[32:47]
	ds_read_b128 v[2:5], v2 offset:4096
	ds_read_b128 v[6:9], v154 offset:16384
	v_max_f32_e32 v189, v97, v97
	s_waitcnt lgkmcnt(0)
	v_mfma_f32_32x32x16_f16 v[112:127], v[2:5], v[6:9], v[230:245]
	v_add_u32_e32 v2, v172, v155
	ds_read_b128 v[190:193], v2 offset:4096
	ds_read_b128 v[2:5], v154 offset:24576
	s_waitcnt lgkmcnt(0)
	v_mfma_f32_32x32x16_f16 v[112:127], v[190:193], v[2:5], v[112:127]
	v_max_f32_e32 v190, v96, v96
	v_max_f32_e32 v189, v190, v189
	v_max3_f32 v189, v189, v98, v99
	v_max3_f32 v189, v189, v100, v101
	v_max3_f32 v189, v189, v102, v103
	v_max3_f32 v189, v189, v104, v105
	v_max3_f32 v189, v189, v106, v107
	v_max3_f32 v189, v189, v108, v109
	v_max3_f32 v189, v189, v110, v111
	v_cmp_lt_f32_e32 vcc, s61, v189
	s_cbranch_vccz .LBB0_896
	ds_bpermute_b32 v190, v153, v189
	s_waitcnt lgkmcnt(0)
	v_max_f32_e32 v190, v190, v190
	v_max_f32_e32 v189, v189, v190
	v_max_f32_e32 v189, v189, v189
	v_max_f32_e32 v190, 0, v189
	v_exp_f32_e64 v192, -v190
	v_add_f32_e32 v168, v168, v190
	v_pk_add_f32 v[96:97], v[96:97], v[190:191] op_sel_hi:[1,0] neg_lo:[0,1] neg_hi:[0,1]
	v_pk_add_f32 v[98:99], v[98:99], v[190:191] op_sel_hi:[1,0] neg_lo:[0,1] neg_hi:[0,1]
	v_mul_f32_e32 v170, v170, v192
	v_pk_add_f32 v[100:101], v[100:101], v[190:191] op_sel_hi:[1,0] neg_lo:[0,1] neg_hi:[0,1]
	v_pk_add_f32 v[102:103], v[102:103], v[190:191] op_sel_hi:[1,0] neg_lo:[0,1] neg_hi:[0,1]
	v_pk_add_f32 v[104:105], v[104:105], v[190:191] op_sel_hi:[1,0] neg_lo:[0,1] neg_hi:[0,1]
	v_pk_add_f32 v[106:107], v[106:107], v[190:191] op_sel_hi:[1,0] neg_lo:[0,1] neg_hi:[0,1]
	v_pk_add_f32 v[108:109], v[108:109], v[190:191] op_sel_hi:[1,0] neg_lo:[0,1] neg_hi:[0,1]
	v_pk_add_f32 v[110:111], v[110:111], v[190:191] op_sel_hi:[1,0] neg_lo:[0,1] neg_hi:[0,1]
	v_sub_f32_e32 v127, v127, v190
	v_sub_f32_e32 v126, v126, v190
	v_sub_f32_e32 v125, v125, v190
	v_sub_f32_e32 v124, v124, v190
	v_sub_f32_e32 v123, v123, v190
	v_sub_f32_e32 v122, v122, v190
	v_sub_f32_e32 v121, v121, v190
	v_sub_f32_e32 v120, v120, v190
	v_sub_f32_e32 v119, v119, v190
	v_sub_f32_e32 v118, v118, v190
	v_sub_f32_e32 v117, v117, v190
	v_sub_f32_e32 v116, v116, v190
	v_sub_f32_e32 v115, v115, v190
	v_sub_f32_e32 v114, v114, v190
	v_sub_f32_e32 v113, v113, v190
	v_sub_f32_e32 v112, v112, v190
	v_pk_mul_f32 v[62:63], v[62:63], v[192:193] op_sel_hi:[1,0]
	v_pk_mul_f32 v[60:61], v[60:61], v[192:193] op_sel_hi:[1,0]
	v_pk_mul_f32 v[58:59], v[58:59], v[192:193] op_sel_hi:[1,0]
	v_pk_mul_f32 v[56:57], v[56:57], v[192:193] op_sel_hi:[1,0]
	v_pk_mul_f32 v[54:55], v[54:55], v[192:193] op_sel_hi:[1,0]
	v_pk_mul_f32 v[52:53], v[52:53], v[192:193] op_sel_hi:[1,0]
	v_pk_mul_f32 v[50:51], v[50:51], v[192:193] op_sel_hi:[1,0]
	v_pk_mul_f32 v[48:49], v[48:49], v[192:193] op_sel_hi:[1,0]
	v_pk_mul_f32 v[78:79], v[78:79], v[192:193] op_sel_hi:[1,0]
	v_pk_mul_f32 v[76:77], v[76:77], v[192:193] op_sel_hi:[1,0]
	v_pk_mul_f32 v[74:75], v[74:75], v[192:193] op_sel_hi:[1,0]
	v_pk_mul_f32 v[72:73], v[72:73], v[192:193] op_sel_hi:[1,0]
	v_pk_mul_f32 v[70:71], v[70:71], v[192:193] op_sel_hi:[1,0]
	v_pk_mul_f32 v[68:69], v[68:69], v[192:193] op_sel_hi:[1,0]
	v_pk_mul_f32 v[66:67], v[66:67], v[192:193] op_sel_hi:[1,0]
	v_pk_mul_f32 v[64:65], v[64:65], v[192:193] op_sel_hi:[1,0]
	v_sub_f32_e32 v230, v230, v190
	v_sub_f32_e32 v231, v231, v190
	v_sub_f32_e32 v232, v232, v190
	v_sub_f32_e32 v233, v233, v190
	v_sub_f32_e32 v234, v234, v190
	v_sub_f32_e32 v235, v235, v190
	v_sub_f32_e32 v236, v236, v190
	v_sub_f32_e32 v237, v237, v190
	v_sub_f32_e32 v238, v238, v190
	v_sub_f32_e32 v239, v239, v190
	v_sub_f32_e32 v240, v240, v190
	v_sub_f32_e32 v241, v241, v190
	v_sub_f32_e32 v242, v242, v190
	v_sub_f32_e32 v243, v243, v190
	v_sub_f32_e32 v244, v244, v190
	v_sub_f32_e32 v245, v245, v190
	s_nop 1
.LBB0_896:
	v_add_f32_e32 v173, 0, v173
	v_add_f32_e32 v173, v174, v173
	v_add_f32_e32 v173, v175, v173
	v_add_f32_e32 v173, v176, v173
	v_add_f32_e32 v173, v177, v173
	v_add_f32_e32 v173, v178, v173
	v_add_f32_e32 v173, v179, v173
	v_add_f32_e32 v173, v180, v173
	v_add_f32_e32 v173, v181, v173
	v_add_f32_e32 v173, v182, v173
	v_add_f32_e32 v173, v183, v173
	v_add_f32_e32 v173, v184, v173
	v_add_f32_e32 v173, v185, v173
	v_exp_f32_e32 v96, v96
	v_exp_f32_e32 v97, v97
	v_exp_f32_e32 v98, v98
	v_exp_f32_e32 v99, v99
	v_exp_f32_e32 v100, v100
	v_exp_f32_e32 v101, v101
	v_exp_f32_e32 v102, v102
	v_exp_f32_e32 v103, v103
	v_add_f32_e32 v173, v186, v173
	v_add_f32_e32 v173, v187, v173
	v_add_f32_e32 v173, v188, v173
	v_add_f32_e32 v171, v171, v173
	v_add_u32_e32 v173, s11, v159
	v_cvt_pkrtz_f16_f32 v174, v96, v97
	v_cvt_pkrtz_f16_f32 v175, v98, v99
	v_cvt_pkrtz_f16_f32 v176, v100, v101
	v_cvt_pkrtz_f16_f32 v177, v102, v103
	v_exp_f32_e32 v104, v104
	v_exp_f32_e32 v105, v105
	v_mfma_f32_32x32x16_f16 v[48:63], v[92:95], v[174:177], v[48:63]
	v_exp_f32_e32 v106, v106
	v_exp_f32_e32 v107, v107
	v_exp_f32_e32 v108, v108
	v_exp_f32_e32 v109, v109
	v_exp_f32_e32 v110, v110
	v_exp_f32_e32 v111, v111
	v_cvt_pkrtz_f16_f32 v178, v104, v105
	v_mfma_f32_32x32x16_f16 v[64:79], v[84:87], v[174:177], v[64:79]
	v_add_u32_e32 v174, v173, v158
	ds_read_b128 v[174:177], v174
	v_cvt_pkrtz_f16_f32 v179, v106, v107
	v_cvt_pkrtz_f16_f32 v180, v108, v109
	v_cvt_pkrtz_f16_f32 v181, v110, v111
	s_nop 1
	v_mfma_f32_32x32x16_f16 v[64:79], v[80:83], v[178:181], v[64:79]
	v_mfma_f32_32x32x16_f16 v[48:63], v[88:91], v[178:181], v[48:63]
	v_add_u32_e32 v178, v173, v160
	s_waitcnt lgkmcnt(0)
	s_nop 0
	v_mfma_f32_32x32x16_f16 v[80:95], v[174:177], v[144:147], v[194:209]
	ds_read_b128 v[144:147], v178
	s_waitcnt lgkmcnt(0)
	v_mfma_f32_32x32x16_f16 v[80:95], v[144:147], v[10:13], v[80:95]
	v_max_f32_e32 v10, v129, v129
	v_max_f32_e32 v11, v128, v128
	v_max_f32_e32 v10, v11, v10
	v_max3_f32 v10, v10, v130, v131
	v_max3_f32 v10, v10, v132, v133
	v_max3_f32 v10, v10, v134, v135
	v_max3_f32 v10, v10, v136, v137
	v_max3_f32 v10, v10, v138, v139
	v_max3_f32 v10, v10, v140, v141
	v_max3_f32 v10, v10, v142, v143
	v_cmp_lt_f32_e32 vcc, s61, v10
	s_cbranch_vccz .LBB0_898
	ds_bpermute_b32 v11, v153, v10
	s_waitcnt lgkmcnt(0)
	v_max_f32_e32 v11, v11, v11
	v_max_f32_e32 v10, v10, v11
	v_max_f32_e32 v10, v10, v10
	v_max_f32_e32 v10, 0, v10
	v_exp_f32_e64 v12, -v10
	v_add_f32_e32 v169, v169, v10
	v_pk_add_f32 v[128:129], v[128:129], v[10:11] op_sel_hi:[1,0] neg_lo:[0,1] neg_hi:[0,1]
	v_pk_add_f32 v[130:131], v[130:131], v[10:11] op_sel_hi:[1,0] neg_lo:[0,1] neg_hi:[0,1]
	v_mul_f32_e32 v171, v171, v12
	v_pk_add_f32 v[132:133], v[132:133], v[10:11] op_sel_hi:[1,0] neg_lo:[0,1] neg_hi:[0,1]
	v_pk_add_f32 v[134:135], v[134:135], v[10:11] op_sel_hi:[1,0] neg_lo:[0,1] neg_hi:[0,1]
	v_pk_add_f32 v[136:137], v[136:137], v[10:11] op_sel_hi:[1,0] neg_lo:[0,1] neg_hi:[0,1]
	v_pk_add_f32 v[138:139], v[138:139], v[10:11] op_sel_hi:[1,0] neg_lo:[0,1] neg_hi:[0,1]
	v_pk_add_f32 v[140:141], v[140:141], v[10:11] op_sel_hi:[1,0] neg_lo:[0,1] neg_hi:[0,1]
	v_pk_add_f32 v[142:143], v[142:143], v[10:11] op_sel_hi:[1,0] neg_lo:[0,1] neg_hi:[0,1]
	v_sub_f32_e32 v95, v95, v10
	v_sub_f32_e32 v94, v94, v10
	v_sub_f32_e32 v93, v93, v10
	v_sub_f32_e32 v92, v92, v10
	v_sub_f32_e32 v91, v91, v10
	v_sub_f32_e32 v90, v90, v10
	v_sub_f32_e32 v89, v89, v10
	v_sub_f32_e32 v88, v88, v10
	v_sub_f32_e32 v87, v87, v10
	v_sub_f32_e32 v86, v86, v10
	v_sub_f32_e32 v85, v85, v10
	v_sub_f32_e32 v84, v84, v10
	v_sub_f32_e32 v83, v83, v10
	v_sub_f32_e32 v82, v82, v10
	v_sub_f32_e32 v81, v81, v10
	v_sub_f32_e32 v80, v80, v10
	v_pk_mul_f32 v[30:31], v[30:31], v[12:13] op_sel_hi:[1,0]
	v_pk_mul_f32 v[28:29], v[28:29], v[12:13] op_sel_hi:[1,0]
	v_pk_mul_f32 v[26:27], v[26:27], v[12:13] op_sel_hi:[1,0]
	v_pk_mul_f32 v[24:25], v[24:25], v[12:13] op_sel_hi:[1,0]
	v_pk_mul_f32 v[22:23], v[22:23], v[12:13] op_sel_hi:[1,0]
	v_pk_mul_f32 v[20:21], v[20:21], v[12:13] op_sel_hi:[1,0]
	v_pk_mul_f32 v[18:19], v[18:19], v[12:13] op_sel_hi:[1,0]
	v_pk_mul_f32 v[16:17], v[16:17], v[12:13] op_sel_hi:[1,0]
	v_pk_mul_f32 v[46:47], v[46:47], v[12:13] op_sel_hi:[1,0]
	v_pk_mul_f32 v[44:45], v[44:45], v[12:13] op_sel_hi:[1,0]
	v_pk_mul_f32 v[42:43], v[42:43], v[12:13] op_sel_hi:[1,0]
	v_pk_mul_f32 v[40:41], v[40:41], v[12:13] op_sel_hi:[1,0]
	v_pk_mul_f32 v[38:39], v[38:39], v[12:13] op_sel_hi:[1,0]
	v_pk_mul_f32 v[36:37], v[36:37], v[12:13] op_sel_hi:[1,0]
	v_pk_mul_f32 v[34:35], v[34:35], v[12:13] op_sel_hi:[1,0]
	v_pk_mul_f32 v[32:33], v[32:33], v[12:13] op_sel_hi:[1,0]
	v_sub_f32_e32 v194, v194, v10
	v_sub_f32_e32 v195, v195, v10
	v_sub_f32_e32 v196, v196, v10
	v_sub_f32_e32 v197, v197, v10
	v_sub_f32_e32 v198, v198, v10
	v_sub_f32_e32 v199, v199, v10
	v_sub_f32_e32 v200, v200, v10
	v_sub_f32_e32 v201, v201, v10
	v_sub_f32_e32 v202, v202, v10
	v_sub_f32_e32 v203, v203, v10
	v_sub_f32_e32 v204, v204, v10
	v_sub_f32_e32 v205, v205, v10
	v_sub_f32_e32 v206, v206, v10
	v_sub_f32_e32 v207, v207, v10
	v_sub_f32_e32 v208, v208, v10
	v_sub_f32_e32 v209, v209, v10
	s_nop 1
.LBB0_898:
	v_add_f32_e32 v10, 0, v96
	v_add_f32_e32 v10, v97, v10
	v_add_f32_e32 v10, v98, v10
	v_add_f32_e32 v10, v99, v10
	v_add_f32_e32 v10, v100, v10
	v_add_f32_e32 v10, v101, v10
	v_add_f32_e32 v10, v102, v10
	v_add_f32_e32 v10, v103, v10
	v_add_f32_e32 v10, v104, v10
	v_add_f32_e32 v10, v105, v10
	v_add_f32_e32 v10, v106, v10
	v_add_f32_e32 v10, v107, v10
	v_add_f32_e32 v10, v108, v10
	v_add_f32_e32 v10, v109, v10
	v_add_f32_e32 v10, v110, v10
	v_add_f32_e32 v10, v111, v10
	v_add_f32_e32 v144, v170, v10
	v_add_u32_e32 v10, v172, v166
	ds_read2st64_b64 v[104:107], v10 offset0:16 offset1:24
	v_add_u32_e32 v10, v172, v167
	v_exp_f32_e32 v145, v128
	v_exp_f32_e32 v146, v129
	v_exp_f32_e32 v147, v130
	v_exp_f32_e32 v170, v131
	ds_read2st64_b64 v[128:131], v10 offset0:16 offset1:24
	v_exp_f32_e32 v174, v132
	v_exp_f32_e32 v175, v133
	v_exp_f32_e32 v176, v134
	v_exp_f32_e32 v177, v135
	v_exp_f32_e32 v178, v136
	v_exp_f32_e32 v179, v137
	v_exp_f32_e32 v180, v138
	v_exp_f32_e32 v181, v139
	s_waitcnt lgkmcnt(0)
	v_mov_b32_e32 v136, v104
	v_mov_b32_e32 v137, v105
	v_mov_b32_e32 v138, v128
	v_mov_b32_e32 v139, v129
	v_mov_b32_e32 v128, v106
	v_mov_b32_e32 v129, v107
	v_add_u32_e32 v10, v172, v1
	ds_read2st64_b64 v[108:111], v10 offset0:16 offset1:24
	v_add_u32_e32 v10, v172, v165
	ds_read2st64_b64 v[10:13], v10 offset0:16 offset1:24
	v_cvt_pkrtz_f16_f32 v96, v145, v146
	v_cvt_pkrtz_f16_f32 v97, v147, v170
	v_cvt_pkrtz_f16_f32 v98, v174, v175
	v_cvt_pkrtz_f16_f32 v99, v176, v177
	v_add_u32_e32 v172, v173, v155
	v_add_u32_e32 v173, v173, v156
	v_mfma_f32_32x32x16_f16 v[16:31], v[136:139], v[96:99], v[16:31]
	ds_read_b128 v[182:185], v173
	v_exp_f32_e32 v140, v140
	v_exp_f32_e32 v141, v141
	v_exp_f32_e32 v142, v142
	v_exp_f32_e32 v143, v143
	s_waitcnt lgkmcnt(0)
	v_mov_b32_e32 v132, v108
	v_mov_b32_e32 v133, v109
	v_mfma_f32_32x32x16_f16 v[32:47], v[128:131], v[96:99], v[32:47]
	v_mov_b32_e32 v134, v10
	v_mov_b32_e32 v135, v11
	v_mov_b32_e32 v10, v110
	v_mov_b32_e32 v11, v111
	v_cvt_pkrtz_f16_f32 v100, v178, v179
	v_cvt_pkrtz_f16_f32 v101, v180, v181
	v_cvt_pkrtz_f16_f32 v102, v140, v141
	v_cvt_pkrtz_f16_f32 v103, v142, v143
	s_nop 1
	v_mfma_f32_32x32x16_f16 v[16:31], v[132:135], v[100:103], v[16:31]
	s_nop 0
	v_mfma_f32_32x32x16_f16 v[32:47], v[10:13], v[100:103], v[32:47]
	s_nop 1
	v_mfma_f32_32x32x16_f16 v[96:111], v[182:185], v[6:9], v[230:245]
	ds_read_b128 v[6:9], v172
	s_waitcnt lgkmcnt(0)
	v_mfma_f32_32x32x16_f16 v[96:111], v[6:9], v[2:5], v[96:111]
	v_max_f32_e32 v2, v113, v113
	v_max_f32_e32 v3, v112, v112
	v_max_f32_e32 v2, v3, v2
	v_max3_f32 v2, v2, v114, v115
	v_max3_f32 v2, v2, v116, v117
	v_max3_f32 v2, v2, v118, v119
	v_max3_f32 v2, v2, v120, v121
	v_max3_f32 v2, v2, v122, v123
	v_max3_f32 v2, v2, v124, v125
	v_max3_f32 v2, v2, v126, v127
	v_cmp_lt_f32_e32 vcc, s61, v2
	s_cbranch_vccz .LBB0_900
	ds_bpermute_b32 v3, v153, v2
	s_waitcnt lgkmcnt(0)
	v_max_f32_e32 v3, v3, v3
	v_max_f32_e32 v2, v2, v3
	v_max_f32_e32 v2, v2, v2
	v_max_f32_e32 v2, 0, v2
	v_exp_f32_e64 v4, -v2
	v_add_f32_e32 v168, v168, v2
	v_pk_add_f32 v[112:113], v[112:113], v[2:3] op_sel_hi:[1,0] neg_lo:[0,1] neg_hi:[0,1]
	v_pk_add_f32 v[114:115], v[114:115], v[2:3] op_sel_hi:[1,0] neg_lo:[0,1] neg_hi:[0,1]
	v_mul_f32_e32 v144, v144, v4
	v_pk_add_f32 v[116:117], v[116:117], v[2:3] op_sel_hi:[1,0] neg_lo:[0,1] neg_hi:[0,1]
	v_pk_add_f32 v[118:119], v[118:119], v[2:3] op_sel_hi:[1,0] neg_lo:[0,1] neg_hi:[0,1]
	v_pk_add_f32 v[120:121], v[120:121], v[2:3] op_sel_hi:[1,0] neg_lo:[0,1] neg_hi:[0,1]
	v_pk_add_f32 v[122:123], v[122:123], v[2:3] op_sel_hi:[1,0] neg_lo:[0,1] neg_hi:[0,1]
	v_pk_add_f32 v[124:125], v[124:125], v[2:3] op_sel_hi:[1,0] neg_lo:[0,1] neg_hi:[0,1]
	v_pk_add_f32 v[126:127], v[126:127], v[2:3] op_sel_hi:[1,0] neg_lo:[0,1] neg_hi:[0,1]
	v_sub_f32_e32 v111, v111, v2
	v_sub_f32_e32 v110, v110, v2
	v_sub_f32_e32 v109, v109, v2
	v_sub_f32_e32 v108, v108, v2
	v_sub_f32_e32 v107, v107, v2
	v_sub_f32_e32 v106, v106, v2
	v_sub_f32_e32 v105, v105, v2
	v_sub_f32_e32 v104, v104, v2
	v_sub_f32_e32 v103, v103, v2
	v_sub_f32_e32 v102, v102, v2
	v_sub_f32_e32 v101, v101, v2
	v_sub_f32_e32 v100, v100, v2
	v_sub_f32_e32 v99, v99, v2
	v_sub_f32_e32 v98, v98, v2
	v_sub_f32_e32 v97, v97, v2
	v_sub_f32_e32 v96, v96, v2
	v_pk_mul_f32 v[62:63], v[62:63], v[4:5] op_sel_hi:[1,0]
	v_pk_mul_f32 v[60:61], v[60:61], v[4:5] op_sel_hi:[1,0]
	v_pk_mul_f32 v[58:59], v[58:59], v[4:5] op_sel_hi:[1,0]
	v_pk_mul_f32 v[56:57], v[56:57], v[4:5] op_sel_hi:[1,0]
	v_pk_mul_f32 v[54:55], v[54:55], v[4:5] op_sel_hi:[1,0]
	v_pk_mul_f32 v[52:53], v[52:53], v[4:5] op_sel_hi:[1,0]
	v_pk_mul_f32 v[50:51], v[50:51], v[4:5] op_sel_hi:[1,0]
	v_pk_mul_f32 v[48:49], v[48:49], v[4:5] op_sel_hi:[1,0]
	v_pk_mul_f32 v[78:79], v[78:79], v[4:5] op_sel_hi:[1,0]
	v_pk_mul_f32 v[76:77], v[76:77], v[4:5] op_sel_hi:[1,0]
	v_pk_mul_f32 v[74:75], v[74:75], v[4:5] op_sel_hi:[1,0]
	v_pk_mul_f32 v[72:73], v[72:73], v[4:5] op_sel_hi:[1,0]
	v_pk_mul_f32 v[70:71], v[70:71], v[4:5] op_sel_hi:[1,0]
	v_pk_mul_f32 v[68:69], v[68:69], v[4:5] op_sel_hi:[1,0]
	v_pk_mul_f32 v[66:67], v[66:67], v[4:5] op_sel_hi:[1,0]
	v_pk_mul_f32 v[64:65], v[64:65], v[4:5] op_sel_hi:[1,0]
	v_sub_f32_e32 v230, v230, v2
	v_sub_f32_e32 v231, v231, v2
	v_sub_f32_e32 v232, v232, v2
	v_sub_f32_e32 v233, v233, v2
	v_sub_f32_e32 v234, v234, v2
	v_sub_f32_e32 v235, v235, v2
	v_sub_f32_e32 v236, v236, v2
	v_sub_f32_e32 v237, v237, v2
	v_sub_f32_e32 v238, v238, v2
	v_sub_f32_e32 v239, v239, v2
	v_sub_f32_e32 v240, v240, v2
	v_sub_f32_e32 v241, v241, v2
	v_sub_f32_e32 v242, v242, v2
	v_sub_f32_e32 v243, v243, v2
	v_sub_f32_e32 v244, v244, v2
	v_sub_f32_e32 v245, v245, v2
	s_nop 1

.LBB0_902:
	v_lshl_or_b32 v14, s10, 14, v159
	v_add_u32_e32 v10, v14, v158
	ds_read_b128 v[2:5], v157 offset:57344
	ds_read_b128 v[6:9], v157 offset:49152
	ds_read_b128 v[10:13], v10 offset:4096
	s_waitcnt lgkmcnt(0)
	s_nop 0
	v_mfma_f32_32x32x16_f16 v[112:127], v[10:13], v[6:9], v[194:209]
	v_add_u32_e32 v6, v14, v160
	ds_read_b128 v[6:9], v6 offset:4096
	v_max_f32_e32 v10, v81, v81
	v_max_f32_e32 v11, v80, v80
	v_max_f32_e32 v10, v11, v10
	v_max3_f32 v10, v10, v82, v83
	v_max3_f32 v10, v10, v84, v85
	v_max3_f32 v10, v10, v86, v87
	v_max3_f32 v10, v10, v88, v89
	v_max3_f32 v10, v10, v90, v91
	v_max3_f32 v10, v10, v92, v93
	v_max3_f32 v10, v10, v94, v95
	ds_bpermute_b32 v11, v153, v10
	s_waitcnt lgkmcnt(1)
	v_mfma_f32_32x32x16_f16 v[112:127], v[6:9], v[2:5], v[112:127]
	s_waitcnt lgkmcnt(0)
	v_max_f32_e32 v2, v11, v11
	v_max_f32_e32 v2, v10, v2
	v_cmp_lt_f32_e32 vcc, s61, v2
	s_cbranch_vccz .LBB0_904
	v_max_f32_e32 v2, v2, v2
	v_max_f32_e32 v2, 0, v2
	v_exp_f32_e64 v4, -v2
	v_pk_add_f32 v[80:81], v[80:81], v[2:3] op_sel_hi:[1,0] neg_lo:[0,1] neg_hi:[0,1]
	v_pk_add_f32 v[82:83], v[82:83], v[2:3] op_sel_hi:[1,0] neg_lo:[0,1] neg_hi:[0,1]
	v_pk_add_f32 v[84:85], v[84:85], v[2:3] op_sel_hi:[1,0] neg_lo:[0,1] neg_hi:[0,1]
	v_mul_f32_e32 v171, v171, v4
	v_pk_add_f32 v[86:87], v[86:87], v[2:3] op_sel_hi:[1,0] neg_lo:[0,1] neg_hi:[0,1]
	v_pk_add_f32 v[88:89], v[88:89], v[2:3] op_sel_hi:[1,0] neg_lo:[0,1] neg_hi:[0,1]
	v_pk_add_f32 v[90:91], v[90:91], v[2:3] op_sel_hi:[1,0] neg_lo:[0,1] neg_hi:[0,1]
	v_pk_add_f32 v[92:93], v[92:93], v[2:3] op_sel_hi:[1,0] neg_lo:[0,1] neg_hi:[0,1]
	v_pk_add_f32 v[94:95], v[94:95], v[2:3] op_sel_hi:[1,0] neg_lo:[0,1] neg_hi:[0,1]
	v_sub_f32_e32 v127, v127, v2
	v_sub_f32_e32 v126, v126, v2
	v_sub_f32_e32 v125, v125, v2
	v_sub_f32_e32 v124, v124, v2
	v_sub_f32_e32 v123, v123, v2
	v_sub_f32_e32 v122, v122, v2
	v_sub_f32_e32 v121, v121, v2
	v_sub_f32_e32 v120, v120, v2
	v_sub_f32_e32 v119, v119, v2
	v_sub_f32_e32 v118, v118, v2
	v_sub_f32_e32 v117, v117, v2
	v_sub_f32_e32 v116, v116, v2
	v_sub_f32_e32 v115, v115, v2
	v_sub_f32_e32 v114, v114, v2
	v_sub_f32_e32 v113, v113, v2
	v_sub_f32_e32 v112, v112, v2
	v_pk_mul_f32 v[30:31], v[30:31], v[4:5] op_sel_hi:[1,0]
	v_pk_mul_f32 v[28:29], v[28:29], v[4:5] op_sel_hi:[1,0]
	v_pk_mul_f32 v[26:27], v[26:27], v[4:5] op_sel_hi:[1,0]
	v_pk_mul_f32 v[24:25], v[24:25], v[4:5] op_sel_hi:[1,0]
	v_pk_mul_f32 v[22:23], v[22:23], v[4:5] op_sel_hi:[1,0]
	v_pk_mul_f32 v[20:21], v[20:21], v[4:5] op_sel_hi:[1,0]
	v_pk_mul_f32 v[18:19], v[18:19], v[4:5] op_sel_hi:[1,0]
	v_pk_mul_f32 v[16:17], v[16:17], v[4:5] op_sel_hi:[1,0]
	v_pk_mul_f32 v[46:47], v[46:47], v[4:5] op_sel_hi:[1,0]
	v_pk_mul_f32 v[44:45], v[44:45], v[4:5] op_sel_hi:[1,0]
	v_pk_mul_f32 v[42:43], v[42:43], v[4:5] op_sel_hi:[1,0]
	v_pk_mul_f32 v[40:41], v[40:41], v[4:5] op_sel_hi:[1,0]
	v_pk_mul_f32 v[38:39], v[38:39], v[4:5] op_sel_hi:[1,0]
	v_pk_mul_f32 v[36:37], v[36:37], v[4:5] op_sel_hi:[1,0]
	v_pk_mul_f32 v[34:35], v[34:35], v[4:5] op_sel_hi:[1,0]
	v_pk_mul_f32 v[32:33], v[32:33], v[4:5] op_sel_hi:[1,0]
.LBB0_904:
	v_add_u32_e32 v2, v14, v161
	v_exp_f32_e32 v139, v88
	v_exp_f32_e32 v140, v89
	v_exp_f32_e32 v141, v90
	v_exp_f32_e32 v142, v91
	ds_read2st64_b64 v[88:91], v2 offset0:16 offset1:24
	v_add_u32_e32 v2, v14, v162
	ds_read2st64_b64 v[2:5], v2 offset0:16 offset1:24
	v_exp_f32_e32 v143, v92
	v_exp_f32_e32 v144, v93
	v_exp_f32_e32 v145, v94
	v_exp_f32_e32 v146, v95
	s_waitcnt lgkmcnt(0)
	v_mov_b32_e32 v130, v2
	v_add_u32_e32 v2, v14, v163
	ds_read2st64_b64 v[92:95], v2 offset0:16 offset1:24
	v_add_u32_e32 v2, v14, v164
	v_exp_f32_e32 v15, v80
	v_exp_f32_e32 v132, v81
	v_exp_f32_e32 v133, v82
	v_exp_f32_e32 v134, v83
	v_exp_f32_e32 v135, v84
	v_exp_f32_e32 v136, v85
	v_exp_f32_e32 v137, v86
	v_exp_f32_e32 v138, v87
	v_mov_b32_e32 v128, v88
	v_mov_b32_e32 v129, v89
	v_mov_b32_e32 v131, v3
	ds_read2st64_b64 v[6:9], v2 offset0:16 offset1:24
	v_mov_b32_e32 v2, v90
	v_mov_b32_e32 v3, v91
	v_cvt_pkrtz_f16_f32 v80, v15, v132
	v_cvt_pkrtz_f16_f32 v81, v133, v134
	v_cvt_pkrtz_f16_f32 v82, v135, v136
	v_cvt_pkrtz_f16_f32 v83, v137, v138
	s_waitcnt lgkmcnt(1)
	v_mov_b32_e32 v10, v92
	v_mov_b32_e32 v11, v93
	v_mfma_f32_32x32x16_f16 v[16:31], v[128:131], v[80:83], v[16:31]
	s_waitcnt lgkmcnt(0)
	v_mov_b32_e32 v12, v6
	v_mov_b32_e32 v13, v7
	v_mov_b32_e32 v6, v94
	v_mov_b32_e32 v7, v95
	v_add_u32_e32 v147, v14, v156
	ds_read_b128 v[156:159], v147 offset:4096
	ds_read_b128 v[160:163], v154 offset:16384
	v_cvt_pkrtz_f16_f32 v84, v139, v140
	v_mfma_f32_32x32x16_f16 v[32:47], v[2:5], v[80:83], v[32:47]
	v_cvt_pkrtz_f16_f32 v85, v141, v142
	v_cvt_pkrtz_f16_f32 v86, v143, v144
	v_cvt_pkrtz_f16_f32 v87, v145, v146
	s_nop 1
	v_mfma_f32_32x32x16_f16 v[16:31], v[10:13], v[84:87], v[16:31]
	s_nop 0
	v_mfma_f32_32x32x16_f16 v[32:47], v[6:9], v[84:87], v[32:47]
	v_add_u32_e32 v147, v14, v155
	v_max_f32_e32 v150, v96, v96
	s_waitcnt lgkmcnt(0)
	v_mfma_f32_32x32x16_f16 v[80:95], v[156:159], v[160:163], v[230:245]
	ds_read_b128 v[156:159], v147 offset:4096
	ds_read_b128 v[160:163], v154 offset:24576
	v_max_f32_e32 v147, v97, v97
	v_max_f32_e32 v147, v150, v147
	v_max3_f32 v147, v147, v98, v99
	v_max3_f32 v147, v147, v100, v101
	v_max3_f32 v147, v147, v102, v103
	v_max3_f32 v147, v147, v104, v105
	v_max3_f32 v147, v147, v106, v107
	v_max3_f32 v147, v147, v108, v109
	v_max3_f32 v147, v147, v110, v111
	s_waitcnt lgkmcnt(0)
	v_mfma_f32_32x32x16_f16 v[80:95], v[156:159], v[160:163], v[80:95]
	ds_bpermute_b32 v150, v153, v147
	s_waitcnt lgkmcnt(0)
	v_max_f32_e32 v150, v150, v150
	v_max_f32_e32 v147, v147, v150
	v_cmp_lt_f32_e32 vcc, s61, v147
	s_cbranch_vccz .LBB0_906
	v_max_f32_e32 v147, v147, v147
	v_max_f32_e32 v150, 0, v147
	v_exp_f32_e64 v154, -v150
	v_pk_add_f32 v[96:97], v[96:97], v[150:151] op_sel_hi:[1,0] neg_lo:[0,1] neg_hi:[0,1]
	v_pk_add_f32 v[98:99], v[98:99], v[150:151] op_sel_hi:[1,0] neg_lo:[0,1] neg_hi:[0,1]
	v_pk_add_f32 v[100:101], v[100:101], v[150:151] op_sel_hi:[1,0] neg_lo:[0,1] neg_hi:[0,1]
	v_mul_f32_e32 v170, v170, v154
	v_pk_add_f32 v[102:103], v[102:103], v[150:151] op_sel_hi:[1,0] neg_lo:[0,1] neg_hi:[0,1]
	v_pk_add_f32 v[104:105], v[104:105], v[150:151] op_sel_hi:[1,0] neg_lo:[0,1] neg_hi:[0,1]
	v_pk_add_f32 v[106:107], v[106:107], v[150:151] op_sel_hi:[1,0] neg_lo:[0,1] neg_hi:[0,1]
	v_pk_add_f32 v[108:109], v[108:109], v[150:151] op_sel_hi:[1,0] neg_lo:[0,1] neg_hi:[0,1]
	v_pk_add_f32 v[110:111], v[110:111], v[150:151] op_sel_hi:[1,0] neg_lo:[0,1] neg_hi:[0,1]
	v_sub_f32_e32 v95, v95, v150
	v_sub_f32_e32 v94, v94, v150
	v_sub_f32_e32 v93, v93, v150
	v_sub_f32_e32 v92, v92, v150
	v_sub_f32_e32 v91, v91, v150
	v_sub_f32_e32 v90, v90, v150
	v_sub_f32_e32 v89, v89, v150
	v_sub_f32_e32 v88, v88, v150
	v_sub_f32_e32 v87, v87, v150
	v_sub_f32_e32 v86, v86, v150
	v_sub_f32_e32 v85, v85, v150
	v_sub_f32_e32 v84, v84, v150
	v_sub_f32_e32 v83, v83, v150
	v_sub_f32_e32 v82, v82, v150
	v_sub_f32_e32 v81, v81, v150
	v_sub_f32_e32 v80, v80, v150
	v_pk_mul_f32 v[62:63], v[62:63], v[154:155] op_sel_hi:[1,0]
	v_pk_mul_f32 v[60:61], v[60:61], v[154:155] op_sel_hi:[1,0]
	v_pk_mul_f32 v[58:59], v[58:59], v[154:155] op_sel_hi:[1,0]
	v_pk_mul_f32 v[56:57], v[56:57], v[154:155] op_sel_hi:[1,0]
	v_pk_mul_f32 v[54:55], v[54:55], v[154:155] op_sel_hi:[1,0]
	v_pk_mul_f32 v[52:53], v[52:53], v[154:155] op_sel_hi:[1,0]
	v_pk_mul_f32 v[50:51], v[50:51], v[154:155] op_sel_hi:[1,0]
	v_pk_mul_f32 v[48:49], v[48:49], v[154:155] op_sel_hi:[1,0]
	v_pk_mul_f32 v[78:79], v[78:79], v[154:155] op_sel_hi:[1,0]
	v_pk_mul_f32 v[76:77], v[76:77], v[154:155] op_sel_hi:[1,0]
	v_pk_mul_f32 v[74:75], v[74:75], v[154:155] op_sel_hi:[1,0]
	v_pk_mul_f32 v[72:73], v[72:73], v[154:155] op_sel_hi:[1,0]
	v_pk_mul_f32 v[70:71], v[70:71], v[154:155] op_sel_hi:[1,0]
	v_pk_mul_f32 v[68:69], v[68:69], v[154:155] op_sel_hi:[1,0]
	v_pk_mul_f32 v[66:67], v[66:67], v[154:155] op_sel_hi:[1,0]
	v_pk_mul_f32 v[64:65], v[64:65], v[154:155] op_sel_hi:[1,0]
